# v16 + grid-barrier acquire: follower workgroups issue buffer_inv sc1 before their generation spin (overlapped with the wait); the XCD leader keeps its invalidate after the flip
# speedup vs baseline: 1.1706x; 1.0138x over previous
; __device__ __forceinline__ unsigned xb_ld(unsigned* p)              { return __hip_atomic_load(p, __ATOMIC_RELAXED, __HIP_MEMORY_SCOPE_AGENT); }
; __device__ __forceinline__ unsigned xb_add(unsigned* p, unsigned v) { return __hip_atomic_fetch_add(p, v, __ATOMIC_RELAXED, __HIP_MEMORY_SCOPE_AGENT); }
; #define XB_SPIN(cond, bar) do { unsigned _sp = 0; while (cond) { __builtin_amdgcn_s_sleep(1); \
;     if ((++_sp & 255u) == 0u) { if (xb_ld(&(bar)[XB_TMO])) break; if (_sp > XB_SPIN_CAP) { atomicAdd(&(bar)[XB_TMO], 1u); break; } } } } while (0)
; __device__ __forceinline__ void xcd_barrier(const XcdBarrier& b) {
;     ...
;         const unsigned old = xb_add(&bar[XB_XSUB(b.x)], 1u);
;         const unsigned gen = old / nloc;
;         if (old + 1u == (gen + 1u) * nloc) {
;             __builtin_amdgcn_fence(__ATOMIC_RELEASE, "agent");
;             asm volatile("s_waitcnt vmcnt(0)" ::: "memory");
;             const unsigned og = xb_add(&bar[XB_TOP], 1u);
;             const unsigned tg = og / nx;
;             if (og + 1u == (tg + 1u) * nx) xb_add(&bar[XB_TOPGEN], 1u);
;             else XB_SPIN(xb_ld(&bar[XB_TOPGEN]) == tg, bar);
;             __builtin_amdgcn_fence(__ATOMIC_ACQUIRE, "agent");
;             xb_add(&bar[XB_XGEN(b.x)], 1u);
;             asm volatile("s_waitcnt vmcnt(0)" ::: "memory");
;         } else {
;             XB_SPIN(xb_ld(&bar[XB_XGEN(b.x)]) == gen, bar);
.LBB0_586:
	s_lshl_b32 s24, s20, 6
	s_add_i32 s8, s24, 0x500
	s_mov_b32 s9, 0
	s_lshl_b64 s[6:7], s[8:9], 2
	s_add_u32 s6, s4, s6
	s_addc_u32 s7, s5, s7
	v_mov_b32_e32 v4, 0
	v_mov_b32_e32 v2, 1
	global_atomic_add v5, v4, v2, s[6:7] sc0
	v_cvt_f32_u32_e32 v2, v3
	v_sub_u32_e32 v6, 0, v3
	v_rcp_iflag_f32_e32 v2, v2
	s_nop 0
	v_mul_f32_e32 v2, 0x4f7ffffe, v2
	v_cvt_u32_f32_e32 v2, v2
	v_mul_lo_u32 v6, v6, v2
	v_mul_hi_u32 v6, v2, v6
	v_add_u32_e32 v2, v2, v6
	s_waitcnt vmcnt(0)
	v_mul_hi_u32 v2, v5, v2
	v_mul_lo_u32 v6, v2, v3
	v_sub_u32_e32 v6, v5, v6
	v_add_u32_e32 v7, 1, v2
	v_cmp_ge_u32_e32 vcc, v6, v3
	v_add_u32_e32 v5, 1, v5
	s_nop 0
	v_cndmask_b32_e32 v2, v2, v7, vcc
	v_sub_u32_e32 v7, v6, v3
	v_cndmask_b32_e32 v6, v6, v7, vcc
	v_add_u32_e32 v7, 1, v2
	v_cmp_ge_u32_e32 vcc, v6, v3
	s_nop 1
	v_cndmask_b32_e32 v2, v2, v7, vcc
	v_mul_lo_u32 v6, v3, v2
	v_add_u32_e32 v3, v6, v3
	v_cmp_ne_u32_e32 vcc, v5, v3
	s_and_saveexec_b64 s[6:7], vcc
	s_xor_b64 s[6:7], exec, s[6:7]
	s_cbranch_execz .LBB0_600
	s_add_i32 s8, s24, 0x900
	s_lshl_b64 s[8:9], s[8:9], 2
	s_add_u32 s10, s4, s8
	s_addc_u32 s11, s5, s9
	s_waitcnt lgkmcnt(0)
	buffer_inv sc1
	global_load_dword v1, v4, s[10:11] sc1
	s_waitcnt vmcnt(0)
	v_cmp_eq_u32_e32 vcc, v1, v2
	s_and_saveexec_b64 s[8:9], vcc
	s_cbranch_execz .LBB0_599
	s_mov_b32 s22, 1
	s_mov_b64 s[12:13], 0
	v_mov_b32_e32 v1, 0
	s_branch .LBB0_590

; __device__ __forceinline__ unsigned xb_ld(unsigned* p)              { return __hip_atomic_load(p, __ATOMIC_RELAXED, __HIP_MEMORY_SCOPE_AGENT); }
; __device__ __forceinline__ unsigned xb_add(unsigned* p, unsigned v) { return __hip_atomic_fetch_add(p, v, __ATOMIC_RELAXED, __HIP_MEMORY_SCOPE_AGENT); }
; #define XB_SPIN(cond, bar) do { unsigned _sp = 0; while (cond) { __builtin_amdgcn_s_sleep(1); \
;     if ((++_sp & 255u) == 0u) { if (xb_ld(&(bar)[XB_TMO])) break; if (_sp > XB_SPIN_CAP) { atomicAdd(&(bar)[XB_TMO], 1u); break; } } } } while (0)
; __device__ __forceinline__ void xcd_barrier(const XcdBarrier& b) {
;     ...
;         const unsigned old = xb_add(&bar[XB_XSUB(b.x)], 1u);
;         const unsigned gen = old / nloc;
;         if (old + 1u == (gen + 1u) * nloc) {
;             __builtin_amdgcn_fence(__ATOMIC_RELEASE, "agent");
;             asm volatile("s_waitcnt vmcnt(0)" ::: "memory");
;             const unsigned og = xb_add(&bar[XB_TOP], 1u);
;             const unsigned tg = og / nx;
;             if (og + 1u == (tg + 1u) * nx) xb_add(&bar[XB_TOPGEN], 1u);
;             else XB_SPIN(xb_ld(&bar[XB_TOPGEN]) == tg, bar);
;             __builtin_amdgcn_fence(__ATOMIC_ACQUIRE, "agent");
;             xb_add(&bar[XB_XGEN(b.x)], 1u);
;             asm volatile("s_waitcnt vmcnt(0)" ::: "memory");
;         } else {
;             XB_SPIN(xb_ld(&bar[XB_XGEN(b.x)]) == gen, bar);
.LBB0_723:
	s_lshl_b32 s23, s18, 6
	s_add_i32 s92, s23, 0x500
	s_lshl_b64 s[4:5], s[92:93], 2
	s_add_u32 s4, s2, s4
	s_addc_u32 s5, s3, s5
	global_atomic_add v5, v35, v228, s[4:5] sc0
	v_cvt_f32_u32_e32 v3, v4
	v_sub_u32_e32 v6, 0, v4
	v_rcp_iflag_f32_e32 v3, v3
	s_nop 0
	v_mul_f32_e32 v3, 0x4f7ffffe, v3
	v_cvt_u32_f32_e32 v3, v3
	v_mul_lo_u32 v6, v6, v3
	v_mul_hi_u32 v6, v3, v6
	v_add_u32_e32 v3, v3, v6
	s_waitcnt vmcnt(0)
	v_mul_hi_u32 v3, v5, v3
	v_mul_lo_u32 v6, v3, v4
	v_sub_u32_e32 v6, v5, v6
	v_add_u32_e32 v7, 1, v3
	v_cmp_ge_u32_e32 vcc, v6, v4
	v_add_u32_e32 v5, 1, v5
	s_nop 0
	v_cndmask_b32_e32 v3, v3, v7, vcc
	v_sub_u32_e32 v7, v6, v4
	v_cndmask_b32_e32 v6, v6, v7, vcc
	v_add_u32_e32 v7, 1, v3
	v_cmp_ge_u32_e32 vcc, v6, v4
	s_nop 1
	v_cndmask_b32_e32 v3, v3, v7, vcc
	v_mul_lo_u32 v6, v4, v3
	v_add_u32_e32 v4, v6, v4
	v_cmp_ne_u32_e32 vcc, v5, v4
	s_and_saveexec_b64 s[4:5], vcc
	s_xor_b64 s[4:5], exec, s[4:5]
	s_cbranch_execz .LBB0_737
	s_add_i32 s92, s23, 0x900
	s_lshl_b64 s[6:7], s[92:93], 2
	s_add_u32 s8, s2, s6
	s_addc_u32 s9, s3, s7
	s_waitcnt lgkmcnt(0)
	buffer_inv sc1
	global_load_dword v2, v35, s[8:9] sc1
	s_waitcnt vmcnt(0)
	v_cmp_eq_u32_e32 vcc, v2, v3
	s_and_saveexec_b64 s[6:7], vcc
	s_cbranch_execz .LBB0_736
	s_mov_b32 s20, 1
	s_mov_b64 s[10:11], 0
	s_branch .LBB0_727

; __device__ __forceinline__ unsigned xb_ld(unsigned* p)              { return __hip_atomic_load(p, __ATOMIC_RELAXED, __HIP_MEMORY_SCOPE_AGENT); }
; __device__ __forceinline__ unsigned xb_add(unsigned* p, unsigned v) { return __hip_atomic_fetch_add(p, v, __ATOMIC_RELAXED, __HIP_MEMORY_SCOPE_AGENT); }
; #define XB_SPIN(cond, bar) do { unsigned _sp = 0; while (cond) { __builtin_amdgcn_s_sleep(1); \
;     if ((++_sp & 255u) == 0u) { if (xb_ld(&(bar)[XB_TMO])) break; if (_sp > XB_SPIN_CAP) { atomicAdd(&(bar)[XB_TMO], 1u); break; } } } } while (0)
; __device__ __forceinline__ void xcd_barrier(const XcdBarrier& b) {
;     ...
;         const unsigned old = xb_add(&bar[XB_XSUB(b.x)], 1u);
;         const unsigned gen = old / nloc;
;         if (old + 1u == (gen + 1u) * nloc) {
;             __builtin_amdgcn_fence(__ATOMIC_RELEASE, "agent");
;             asm volatile("s_waitcnt vmcnt(0)" ::: "memory");
;             const unsigned og = xb_add(&bar[XB_TOP], 1u);
;             const unsigned tg = og / nx;
;             if (og + 1u == (tg + 1u) * nx) xb_add(&bar[XB_TOPGEN], 1u);
;             else XB_SPIN(xb_ld(&bar[XB_TOPGEN]) == tg, bar);
;             __builtin_amdgcn_fence(__ATOMIC_ACQUIRE, "agent");
;             xb_add(&bar[XB_XGEN(b.x)], 1u);
;             asm volatile("s_waitcnt vmcnt(0)" ::: "memory");
;         } else {
;             XB_SPIN(xb_ld(&bar[XB_XGEN(b.x)]) == gen, bar);
.LBB0_990:
	s_lshl_b32 s25, s20, 6
	s_add_i32 s92, s25, 0x500
	s_lshl_b64 s[6:7], s[92:93], 2
	s_add_u32 s6, s4, s6
	s_addc_u32 s7, s5, s7
	global_atomic_add v5, v35, v228, s[6:7] sc0
	v_cvt_f32_u32_e32 v3, v4
	v_sub_u32_e32 v6, 0, v4
	v_rcp_iflag_f32_e32 v3, v3
	s_nop 0
	v_mul_f32_e32 v3, 0x4f7ffffe, v3
	v_cvt_u32_f32_e32 v3, v3
	v_mul_lo_u32 v6, v6, v3
	v_mul_hi_u32 v6, v3, v6
	v_add_u32_e32 v3, v3, v6
	s_waitcnt vmcnt(0)
	v_mul_hi_u32 v3, v5, v3
	v_mul_lo_u32 v6, v3, v4
	v_sub_u32_e32 v6, v5, v6
	v_add_u32_e32 v7, 1, v3
	v_cmp_ge_u32_e32 vcc, v6, v4
	v_add_u32_e32 v5, 1, v5
	s_nop 0
	v_cndmask_b32_e32 v3, v3, v7, vcc
	v_sub_u32_e32 v7, v6, v4
	v_cndmask_b32_e32 v6, v6, v7, vcc
	v_add_u32_e32 v7, 1, v3
	v_cmp_ge_u32_e32 vcc, v6, v4
	s_nop 1
	v_cndmask_b32_e32 v3, v3, v7, vcc
	v_mul_lo_u32 v6, v4, v3
	v_add_u32_e32 v4, v6, v4
	v_cmp_ne_u32_e32 vcc, v5, v4
	s_and_saveexec_b64 s[6:7], vcc
	s_xor_b64 s[6:7], exec, s[6:7]
	s_cbranch_execz .LBB0_1004
	s_add_i32 s92, s25, 0x900
	s_lshl_b64 s[8:9], s[92:93], 2
	s_add_u32 s10, s4, s8
	s_addc_u32 s11, s5, s9
	s_waitcnt lgkmcnt(0)
	buffer_inv sc1
	global_load_dword v2, v35, s[10:11] sc1
	s_waitcnt vmcnt(0)
	v_cmp_eq_u32_e32 vcc, v2, v3
	s_and_saveexec_b64 s[8:9], vcc
	s_cbranch_execz .LBB0_1003
	s_mov_b32 s22, 1
	s_mov_b64 s[12:13], 0
	s_branch .LBB0_994

; __device__ __forceinline__ unsigned xb_ld(unsigned* p)              { return __hip_atomic_load(p, __ATOMIC_RELAXED, __HIP_MEMORY_SCOPE_AGENT); }
; __device__ __forceinline__ unsigned xb_add(unsigned* p, unsigned v) { return __hip_atomic_fetch_add(p, v, __ATOMIC_RELAXED, __HIP_MEMORY_SCOPE_AGENT); }
; #define XB_SPIN(cond, bar) do { unsigned _sp = 0; while (cond) { __builtin_amdgcn_s_sleep(1); \
;     if ((++_sp & 255u) == 0u) { if (xb_ld(&(bar)[XB_TMO])) break; if (_sp > XB_SPIN_CAP) { atomicAdd(&(bar)[XB_TMO], 1u); break; } } } } while (0)
; __device__ __forceinline__ void xcd_barrier(const XcdBarrier& b) {
;     ...
;         const unsigned old = xb_add(&bar[XB_XSUB(b.x)], 1u);
;         const unsigned gen = old / nloc;
;         if (old + 1u == (gen + 1u) * nloc) {
;             __builtin_amdgcn_fence(__ATOMIC_RELEASE, "agent");
;             asm volatile("s_waitcnt vmcnt(0)" ::: "memory");
;             const unsigned og = xb_add(&bar[XB_TOP], 1u);
;             const unsigned tg = og / nx;
;             if (og + 1u == (tg + 1u) * nx) xb_add(&bar[XB_TOPGEN], 1u);
;             else XB_SPIN(xb_ld(&bar[XB_TOPGEN]) == tg, bar);
;             __builtin_amdgcn_fence(__ATOMIC_ACQUIRE, "agent");
;             xb_add(&bar[XB_XGEN(b.x)], 1u);
;             asm volatile("s_waitcnt vmcnt(0)" ::: "memory");
;         } else {
;             XB_SPIN(xb_ld(&bar[XB_XGEN(b.x)]) == gen, bar);
.LBB0_1568:
	s_lshl_b32 s24, s20, 6
	s_add_i32 s92, s24, 0x500
	s_lshl_b64 s[6:7], s[92:93], 2
	s_add_u32 s6, s2, s6
	s_addc_u32 s7, s3, s7
	global_atomic_add v5, v35, v228, s[6:7] sc0
	v_cvt_f32_u32_e32 v3, v4
	v_sub_u32_e32 v6, 0, v4
	v_rcp_iflag_f32_e32 v3, v3
	s_nop 0
	v_mul_f32_e32 v3, 0x4f7ffffe, v3
	v_cvt_u32_f32_e32 v3, v3
	v_mul_lo_u32 v6, v6, v3
	v_mul_hi_u32 v6, v3, v6
	v_add_u32_e32 v3, v3, v6
	s_waitcnt vmcnt(0)
	v_mul_hi_u32 v3, v5, v3
	v_mul_lo_u32 v6, v3, v4
	v_sub_u32_e32 v6, v5, v6
	v_add_u32_e32 v7, 1, v3
	v_cmp_ge_u32_e32 vcc, v6, v4
	v_add_u32_e32 v5, 1, v5
	s_nop 0
	v_cndmask_b32_e32 v3, v3, v7, vcc
	v_sub_u32_e32 v7, v6, v4
	v_cndmask_b32_e32 v6, v6, v7, vcc
	v_add_u32_e32 v7, 1, v3
	v_cmp_ge_u32_e32 vcc, v6, v4
	s_nop 1
	v_cndmask_b32_e32 v3, v3, v7, vcc
	v_mul_lo_u32 v6, v4, v3
	v_add_u32_e32 v4, v6, v4
	v_cmp_ne_u32_e32 vcc, v5, v4
	s_and_saveexec_b64 s[6:7], vcc
	s_xor_b64 s[6:7], exec, s[6:7]
	s_cbranch_execz .LBB0_1582
	s_add_i32 s92, s24, 0x900
	s_lshl_b64 s[8:9], s[92:93], 2
	s_add_u32 s10, s2, s8
	s_addc_u32 s11, s3, s9
	s_waitcnt lgkmcnt(0)
	buffer_inv sc1
	global_load_dword v2, v35, s[10:11] sc1
	s_waitcnt vmcnt(0)
	v_cmp_eq_u32_e32 vcc, v2, v3
	s_and_saveexec_b64 s[8:9], vcc
	s_cbranch_execz .LBB0_1581
	s_mov_b32 s22, 1
	s_mov_b64 s[12:13], 0
	s_branch .LBB0_1572

; __device__ __forceinline__ unsigned xb_ld(unsigned* p)              { return __hip_atomic_load(p, __ATOMIC_RELAXED, __HIP_MEMORY_SCOPE_AGENT); }
; __device__ __forceinline__ unsigned xb_add(unsigned* p, unsigned v) { return __hip_atomic_fetch_add(p, v, __ATOMIC_RELAXED, __HIP_MEMORY_SCOPE_AGENT); }
; #define XB_SPIN(cond, bar) do { unsigned _sp = 0; while (cond) { __builtin_amdgcn_s_sleep(1); \
;     if ((++_sp & 255u) == 0u) { if (xb_ld(&(bar)[XB_TMO])) break; if (_sp > XB_SPIN_CAP) { atomicAdd(&(bar)[XB_TMO], 1u); break; } } } } while (0)
; __device__ __forceinline__ void xcd_barrier(const XcdBarrier& b) {
;     ...
;         const unsigned old = xb_add(&bar[XB_XSUB(b.x)], 1u);
;         const unsigned gen = old / nloc;
;         if (old + 1u == (gen + 1u) * nloc) {
;             __builtin_amdgcn_fence(__ATOMIC_RELEASE, "agent");
;             asm volatile("s_waitcnt vmcnt(0)" ::: "memory");
;             const unsigned og = xb_add(&bar[XB_TOP], 1u);
;             const unsigned tg = og / nx;
;             if (og + 1u == (tg + 1u) * nx) xb_add(&bar[XB_TOPGEN], 1u);
;             else XB_SPIN(xb_ld(&bar[XB_TOPGEN]) == tg, bar);
;             __builtin_amdgcn_fence(__ATOMIC_ACQUIRE, "agent");
;             xb_add(&bar[XB_XGEN(b.x)], 1u);
;             asm volatile("s_waitcnt vmcnt(0)" ::: "memory");
;         } else {
;             XB_SPIN(xb_ld(&bar[XB_XGEN(b.x)]) == gen, bar);
.LBB0_2095:
	s_lshl_b32 s22, s18, 6
	s_add_i32 s92, s22, 0x500
	s_lshl_b64 s[4:5], s[92:93], 2
	s_add_u32 s4, s2, s4
	s_addc_u32 s5, s3, s5
	global_atomic_add v5, v35, v228, s[4:5] sc0
	v_cvt_f32_u32_e32 v3, v4
	v_sub_u32_e32 v6, 0, v4
	v_rcp_iflag_f32_e32 v3, v3
	s_nop 0
	v_mul_f32_e32 v3, 0x4f7ffffe, v3
	v_cvt_u32_f32_e32 v3, v3
	v_mul_lo_u32 v6, v6, v3
	v_mul_hi_u32 v6, v3, v6
	v_add_u32_e32 v3, v3, v6
	s_waitcnt vmcnt(0)
	v_mul_hi_u32 v3, v5, v3
	v_mul_lo_u32 v6, v3, v4
	v_sub_u32_e32 v6, v5, v6
	v_add_u32_e32 v7, 1, v3
	v_cmp_ge_u32_e32 vcc, v6, v4
	v_add_u32_e32 v5, 1, v5
	s_nop 0
	v_cndmask_b32_e32 v3, v3, v7, vcc
	v_sub_u32_e32 v7, v6, v4
	v_cndmask_b32_e32 v6, v6, v7, vcc
	v_add_u32_e32 v7, 1, v3
	v_cmp_ge_u32_e32 vcc, v6, v4
	s_nop 1
	v_cndmask_b32_e32 v3, v3, v7, vcc
	v_mul_lo_u32 v6, v4, v3
	v_add_u32_e32 v4, v6, v4
	v_cmp_ne_u32_e32 vcc, v5, v4
	s_and_saveexec_b64 s[4:5], vcc
	s_xor_b64 s[4:5], exec, s[4:5]
	s_cbranch_execz .LBB0_2109
	s_add_i32 s92, s22, 0x900
	s_lshl_b64 s[6:7], s[92:93], 2
	s_add_u32 s8, s2, s6
	s_addc_u32 s9, s3, s7
	s_waitcnt lgkmcnt(0)
	buffer_inv sc1
	global_load_dword v2, v35, s[8:9] sc1
	s_waitcnt vmcnt(0)
	v_cmp_eq_u32_e32 vcc, v2, v3
	s_and_saveexec_b64 s[6:7], vcc
	s_cbranch_execz .LBB0_2108
	s_mov_b32 s20, 1
	s_mov_b64 s[10:11], 0
	s_branch .LBB0_2099
